# attention block epilogue rewritten: DPP neighbour exchange instead of 64 ds_bpermute round trips, 32 full-wave stores, no exec masking/branches
# speedup vs baseline: 1.0134x; 1.0018x over previous
; __device__ __forceinline__ int crow(int r, int hi) { return (r & 3) + 8 * (r >> 2) + 4 * hi; }
; template <class TIn, class TOut>
; __device__ __forceinline__ void causal_swa_block(const BlockRef<TIn, TOut>& cur, const BlockRef<TIn, TOut>& nxt, int skv, int W, char* lds, Seam<TIn>& S) {
;     ...
;     if (hi == 0) { li_l[r32] = l_reg; cur.L[(size_t)(wid * QBLK + r32) * (size_t)cur.lpitch] = m_reg * SCALE + __builtin_amdgcn_logf(l_reg) * 0.6931471805599453f; }
;     asm volatile("s_waitcnt lgkmcnt(0)" ::: "memory");
;     float rli[16];
; #pragma unroll
;     for (int r = 0; r < 16; ++r) rli[r] = __builtin_amdgcn_rcpf(li_l[crow(r, hi)]);
;     TOut* Ow = cur.O + (size_t)(wid * QBLK) * (size_t)cur.pitch;
; #pragma unroll
;     for (int r = 0; r < 16; ++r) { const int orow = crow(r, hi);
; #pragma unroll
;         for (int d0 = 0; d0 < 4; ++d0) { const float v = o[d0][r] * rli[r];
;             if constexpr (same_t<TOut, float>::v) { Ow[(size_t)orow * (size_t)cur.pitch + d0 * 32 + r32] = v; }
;             else { const float vn = __shfl_xor(v, 1);
;                    if ((r32 & 1) == 0) *(unsigned*)(Ow + (size_t)orow * (size_t)cur.pitch + d0 * 32 + r32) = cvtpk(v, vn); } } }
.LBB0_290:
	s_or_b64 exec, exec, s[6:7]
	s_waitcnt lgkmcnt(0)
	ds_read_b128 v[80:83], v213
	ds_read_b128 v[10:13], v213 offset:32
	ds_read_b128 v[6:9], v213 offset:64
	ds_read_b128 v[2:5], v213 offset:96
	s_mul_hi_i32 s7, s52, s48
	s_mul_i32 s6, s52, s48
	s_lshl_b64 s[6:7], s[6:7], 1
	s_add_u32 s6, s20, s6
	s_addc_u32 s7, s21, s7
	s_lshl_b32 s10, s48, 1
	s_mul_i32 s11, s10, 5
	v_and_b32_e32 v14, 1, v210
	v_and_b32_e32 v15, 30, v210
	v_mul_lo_u32 v1, v208, s10
	v_lshl_add_u32 v1, v15, 1, v1
	v_lshl_add_u32 v1, v14, 7, v1
	v_cmp_eq_u32_e64 s[8:9], 1, v14
	s_waitcnt lgkmcnt(0)
	v_rcp_f32_e32 v80, v80
	v_rcp_f32_e32 v81, v81
	v_rcp_f32_e32 v82, v82
	v_rcp_f32_e32 v83, v83
	v_rcp_f32_e32 v10, v10
	v_rcp_f32_e32 v11, v11
	v_rcp_f32_e32 v12, v12
	v_rcp_f32_e32 v13, v13
	v_rcp_f32_e32 v6, v6
	v_rcp_f32_e32 v7, v7
	v_rcp_f32_e32 v8, v8
	v_rcp_f32_e32 v9, v9
	v_rcp_f32_e32 v2, v2
	v_rcp_f32_e32 v3, v3
	v_rcp_f32_e32 v4, v4
	v_rcp_f32_e32 v5, v5
	s_nop 0
	v_mul_f32_e32 v64, v64, v80
	v_mul_f32_e32 v48, v48, v80
	v_mul_f32_e32 v32, v32, v80
	v_mul_f32_e32 v16, v16, v80
	v_mul_f32_e32 v65, v65, v81
	v_mul_f32_e32 v49, v49, v81
	v_mul_f32_e32 v33, v33, v81
	v_mul_f32_e32 v17, v17, v81
	v_mul_f32_e32 v66, v66, v82
	v_mul_f32_e32 v50, v50, v82
	v_mul_f32_e32 v34, v34, v82
	v_mul_f32_e32 v18, v18, v82
	v_mul_f32_e32 v67, v67, v83
	v_mul_f32_e32 v51, v51, v83
	v_mul_f32_e32 v35, v35, v83
	v_mul_f32_e32 v19, v19, v83
	v_mul_f32_e32 v68, v68, v10
	v_mul_f32_e32 v52, v52, v10
	v_mul_f32_e32 v36, v36, v10
	v_mul_f32_e32 v20, v20, v10
	v_mul_f32_e32 v69, v69, v11
	v_mul_f32_e32 v53, v53, v11
	v_mul_f32_e32 v37, v37, v11
	v_mul_f32_e32 v21, v21, v11
	v_mul_f32_e32 v70, v70, v12
	v_mul_f32_e32 v54, v54, v12
	v_mul_f32_e32 v38, v38, v12
	v_mul_f32_e32 v22, v22, v12
	v_mul_f32_e32 v71, v71, v13
	v_mul_f32_e32 v55, v55, v13
	v_mul_f32_e32 v39, v39, v13
	v_mul_f32_e32 v23, v23, v13
	v_mul_f32_e32 v72, v72, v6
	v_mul_f32_e32 v56, v56, v6
	v_mul_f32_e32 v40, v40, v6
	v_mul_f32_e32 v24, v24, v6
	v_mul_f32_e32 v73, v73, v7
	v_mul_f32_e32 v57, v57, v7
	v_mul_f32_e32 v41, v41, v7
	v_mul_f32_e32 v25, v25, v7
	v_mul_f32_e32 v74, v74, v8
	v_mul_f32_e32 v58, v58, v8
	v_mul_f32_e32 v42, v42, v8
	v_mul_f32_e32 v26, v26, v8
	v_mul_f32_e32 v75, v75, v9
	v_mul_f32_e32 v59, v59, v9
	v_mul_f32_e32 v43, v43, v9
	v_mul_f32_e32 v27, v27, v9
	v_mul_f32_e32 v76, v76, v2
	v_mul_f32_e32 v60, v60, v2
	v_mul_f32_e32 v44, v44, v2
	v_mul_f32_e32 v28, v28, v2
	v_mul_f32_e32 v77, v77, v3
	v_mul_f32_e32 v61, v61, v3
	v_mul_f32_e32 v45, v45, v3
	v_mul_f32_e32 v29, v29, v3
	v_mul_f32_e32 v78, v78, v4
	v_mul_f32_e32 v62, v62, v4
	v_mul_f32_e32 v46, v46, v4
	v_mul_f32_e32 v30, v30, v4
	v_mul_f32_e32 v79, v79, v5
	v_mul_f32_e32 v63, v63, v5
	v_mul_f32_e32 v47, v47, v5
	v_mul_f32_e32 v31, v31, v5
	v_mov_b32_dpp v84, v64 quad_perm:[1,0,3,2] row_mask:0xf bank_mask:0xf
	v_mov_b32_dpp v85, v32 quad_perm:[1,0,3,2] row_mask:0xf bank_mask:0xf
	v_cndmask_b32_e64 v64, v64, v85, s[8:9]
	v_cndmask_b32_e64 v32, v84, v32, s[8:9]
	v_cvt_pk_bf16_f32 v64, v64, v32
	global_store_dword v1, v64, s[6:7]
	v_mov_b32_dpp v84, v48 quad_perm:[1,0,3,2] row_mask:0xf bank_mask:0xf
	v_mov_b32_dpp v85, v16 quad_perm:[1,0,3,2] row_mask:0xf bank_mask:0xf
	v_cndmask_b32_e64 v48, v48, v85, s[8:9]
	v_cndmask_b32_e64 v16, v84, v16, s[8:9]
	v_cvt_pk_bf16_f32 v48, v48, v16
	global_store_dword v1, v48, s[6:7] offset:64
	v_add_u32_e32 v1, s10, v1
	v_mov_b32_dpp v84, v65 quad_perm:[1,0,3,2] row_mask:0xf bank_mask:0xf
	v_mov_b32_dpp v85, v33 quad_perm:[1,0,3,2] row_mask:0xf bank_mask:0xf
	v_cndmask_b32_e64 v65, v65, v85, s[8:9]
	v_cndmask_b32_e64 v33, v84, v33, s[8:9]
	v_cvt_pk_bf16_f32 v65, v65, v33
	global_store_dword v1, v65, s[6:7]
	v_mov_b32_dpp v84, v49 quad_perm:[1,0,3,2] row_mask:0xf bank_mask:0xf
	v_mov_b32_dpp v85, v17 quad_perm:[1,0,3,2] row_mask:0xf bank_mask:0xf
	v_cndmask_b32_e64 v49, v49, v85, s[8:9]
	v_cndmask_b32_e64 v17, v84, v17, s[8:9]
	v_cvt_pk_bf16_f32 v49, v49, v17
	global_store_dword v1, v49, s[6:7] offset:64
	v_add_u32_e32 v1, s10, v1
	v_mov_b32_dpp v84, v66 quad_perm:[1,0,3,2] row_mask:0xf bank_mask:0xf
	v_mov_b32_dpp v85, v34 quad_perm:[1,0,3,2] row_mask:0xf bank_mask:0xf
	v_cndmask_b32_e64 v66, v66, v85, s[8:9]
	v_cndmask_b32_e64 v34, v84, v34, s[8:9]
	v_cvt_pk_bf16_f32 v66, v66, v34
	global_store_dword v1, v66, s[6:7]
	v_mov_b32_dpp v84, v50 quad_perm:[1,0,3,2] row_mask:0xf bank_mask:0xf
	v_mov_b32_dpp v85, v18 quad_perm:[1,0,3,2] row_mask:0xf bank_mask:0xf
	v_cndmask_b32_e64 v50, v50, v85, s[8:9]
	v_cndmask_b32_e64 v18, v84, v18, s[8:9]
	v_cvt_pk_bf16_f32 v50, v50, v18
	global_store_dword v1, v50, s[6:7] offset:64
	v_add_u32_e32 v1, s10, v1
	v_mov_b32_dpp v84, v67 quad_perm:[1,0,3,2] row_mask:0xf bank_mask:0xf
	v_mov_b32_dpp v85, v35 quad_perm:[1,0,3,2] row_mask:0xf bank_mask:0xf
	v_cndmask_b32_e64 v67, v67, v85, s[8:9]
	v_cndmask_b32_e64 v35, v84, v35, s[8:9]
	v_cvt_pk_bf16_f32 v67, v67, v35
	global_store_dword v1, v67, s[6:7]
	v_mov_b32_dpp v84, v51 quad_perm:[1,0,3,2] row_mask:0xf bank_mask:0xf
	v_mov_b32_dpp v85, v19 quad_perm:[1,0,3,2] row_mask:0xf bank_mask:0xf
	v_cndmask_b32_e64 v51, v51, v85, s[8:9]
	v_cndmask_b32_e64 v19, v84, v19, s[8:9]
	v_cvt_pk_bf16_f32 v51, v51, v19
	global_store_dword v1, v51, s[6:7] offset:64
	v_add_u32_e32 v1, s11, v1
	v_mov_b32_dpp v84, v68 quad_perm:[1,0,3,2] row_mask:0xf bank_mask:0xf
	v_mov_b32_dpp v85, v36 quad_perm:[1,0,3,2] row_mask:0xf bank_mask:0xf
	v_cndmask_b32_e64 v68, v68, v85, s[8:9]
	v_cndmask_b32_e64 v36, v84, v36, s[8:9]
	v_cvt_pk_bf16_f32 v68, v68, v36
	global_store_dword v1, v68, s[6:7]
	v_mov_b32_dpp v84, v52 quad_perm:[1,0,3,2] row_mask:0xf bank_mask:0xf
; __device__ __forceinline__ int crow(int r, int hi) { return (r & 3) + 8 * (r >> 2) + 4 * hi; }
; template <class TIn, class TOut>
; __device__ __forceinline__ void causal_swa_block(const BlockRef<TIn, TOut>& cur, const BlockRef<TIn, TOut>& nxt, int skv, int W, char* lds, Seam<TIn>& S) {
;     ...
;     for (int r = 0; r < 16; ++r) { const int orow = crow(r, hi);
; #pragma unroll
;         for (int d0 = 0; d0 < 4; ++d0) { const float v = o[d0][r] * rli[r];
;             if constexpr (same_t<TOut, float>::v) { Ow[(size_t)orow * (size_t)cur.pitch + d0 * 32 + r32] = v; }
;             else { const float vn = __shfl_xor(v, 1);
;                    if ((r32 & 1) == 0) *(unsigned*)(Ow + (size_t)orow * (size_t)cur.pitch + d0 * 32 + r32) = cvtpk(v, vn); } } }
	v_mov_b32_dpp v85, v20 quad_perm:[1,0,3,2] row_mask:0xf bank_mask:0xf
	v_cndmask_b32_e64 v52, v52, v85, s[8:9]
	v_cndmask_b32_e64 v20, v84, v20, s[8:9]
	v_cvt_pk_bf16_f32 v52, v52, v20
	global_store_dword v1, v52, s[6:7] offset:64
	v_add_u32_e32 v1, s10, v1
	v_mov_b32_dpp v84, v69 quad_perm:[1,0,3,2] row_mask:0xf bank_mask:0xf
	v_mov_b32_dpp v85, v37 quad_perm:[1,0,3,2] row_mask:0xf bank_mask:0xf
	v_cndmask_b32_e64 v69, v69, v85, s[8:9]
	v_cndmask_b32_e64 v37, v84, v37, s[8:9]
	v_cvt_pk_bf16_f32 v69, v69, v37
	global_store_dword v1, v69, s[6:7]
	v_mov_b32_dpp v84, v53 quad_perm:[1,0,3,2] row_mask:0xf bank_mask:0xf
	v_mov_b32_dpp v85, v21 quad_perm:[1,0,3,2] row_mask:0xf bank_mask:0xf
	v_cndmask_b32_e64 v53, v53, v85, s[8:9]
	v_cndmask_b32_e64 v21, v84, v21, s[8:9]
	v_cvt_pk_bf16_f32 v53, v53, v21
	global_store_dword v1, v53, s[6:7] offset:64
	v_add_u32_e32 v1, s10, v1
	v_mov_b32_dpp v84, v70 quad_perm:[1,0,3,2] row_mask:0xf bank_mask:0xf
	v_mov_b32_dpp v85, v38 quad_perm:[1,0,3,2] row_mask:0xf bank_mask:0xf
	v_cndmask_b32_e64 v70, v70, v85, s[8:9]
	v_cndmask_b32_e64 v38, v84, v38, s[8:9]
	v_cvt_pk_bf16_f32 v70, v70, v38
	global_store_dword v1, v70, s[6:7]
	v_mov_b32_dpp v84, v54 quad_perm:[1,0,3,2] row_mask:0xf bank_mask:0xf
	v_mov_b32_dpp v85, v22 quad_perm:[1,0,3,2] row_mask:0xf bank_mask:0xf
	v_cndmask_b32_e64 v54, v54, v85, s[8:9]
	v_cndmask_b32_e64 v22, v84, v22, s[8:9]
	v_cvt_pk_bf16_f32 v54, v54, v22
	global_store_dword v1, v54, s[6:7] offset:64
	v_add_u32_e32 v1, s10, v1
	v_mov_b32_dpp v84, v71 quad_perm:[1,0,3,2] row_mask:0xf bank_mask:0xf
	v_mov_b32_dpp v85, v39 quad_perm:[1,0,3,2] row_mask:0xf bank_mask:0xf
	v_cndmask_b32_e64 v71, v71, v85, s[8:9]
	v_cndmask_b32_e64 v39, v84, v39, s[8:9]
	v_cvt_pk_bf16_f32 v71, v71, v39
	global_store_dword v1, v71, s[6:7]
	v_mov_b32_dpp v84, v55 quad_perm:[1,0,3,2] row_mask:0xf bank_mask:0xf
	v_mov_b32_dpp v85, v23 quad_perm:[1,0,3,2] row_mask:0xf bank_mask:0xf
	v_cndmask_b32_e64 v55, v55, v85, s[8:9]
	v_cndmask_b32_e64 v23, v84, v23, s[8:9]
	v_cvt_pk_bf16_f32 v55, v55, v23
	global_store_dword v1, v55, s[6:7] offset:64
	v_add_u32_e32 v1, s11, v1
	v_mov_b32_dpp v84, v72 quad_perm:[1,0,3,2] row_mask:0xf bank_mask:0xf
	v_mov_b32_dpp v85, v40 quad_perm:[1,0,3,2] row_mask:0xf bank_mask:0xf
	v_cndmask_b32_e64 v72, v72, v85, s[8:9]
	v_cndmask_b32_e64 v40, v84, v40, s[8:9]
	v_cvt_pk_bf16_f32 v72, v72, v40
	global_store_dword v1, v72, s[6:7]
	v_mov_b32_dpp v84, v56 quad_perm:[1,0,3,2] row_mask:0xf bank_mask:0xf
	v_mov_b32_dpp v85, v24 quad_perm:[1,0,3,2] row_mask:0xf bank_mask:0xf
	v_cndmask_b32_e64 v56, v56, v85, s[8:9]
	v_cndmask_b32_e64 v24, v84, v24, s[8:9]
	v_cvt_pk_bf16_f32 v56, v56, v24
	global_store_dword v1, v56, s[6:7] offset:64
	v_add_u32_e32 v1, s10, v1
	v_mov_b32_dpp v84, v73 quad_perm:[1,0,3,2] row_mask:0xf bank_mask:0xf
	v_mov_b32_dpp v85, v41 quad_perm:[1,0,3,2] row_mask:0xf bank_mask:0xf
	v_cndmask_b32_e64 v73, v73, v85, s[8:9]
	v_cndmask_b32_e64 v41, v84, v41, s[8:9]
	v_cvt_pk_bf16_f32 v73, v73, v41
	global_store_dword v1, v73, s[6:7]
	v_mov_b32_dpp v84, v57 quad_perm:[1,0,3,2] row_mask:0xf bank_mask:0xf
	v_mov_b32_dpp v85, v25 quad_perm:[1,0,3,2] row_mask:0xf bank_mask:0xf
	v_cndmask_b32_e64 v57, v57, v85, s[8:9]
	v_cndmask_b32_e64 v25, v84, v25, s[8:9]
	v_cvt_pk_bf16_f32 v57, v57, v25
	global_store_dword v1, v57, s[6:7] offset:64
	v_add_u32_e32 v1, s10, v1
	v_mov_b32_dpp v84, v74 quad_perm:[1,0,3,2] row_mask:0xf bank_mask:0xf
	v_mov_b32_dpp v85, v42 quad_perm:[1,0,3,2] row_mask:0xf bank_mask:0xf
	v_cndmask_b32_e64 v74, v74, v85, s[8:9]
	v_cndmask_b32_e64 v42, v84, v42, s[8:9]
	v_cvt_pk_bf16_f32 v74, v74, v42
; __device__ __forceinline__ int crow(int r, int hi) { return (r & 3) + 8 * (r >> 2) + 4 * hi; }
; template <class TIn, class TOut>
; __device__ __forceinline__ void causal_swa_block(const BlockRef<TIn, TOut>& cur, const BlockRef<TIn, TOut>& nxt, int skv, int W, char* lds, Seam<TIn>& S) {
;     ...
;     for (int r = 0; r < 16; ++r) { const int orow = crow(r, hi);
; #pragma unroll
;         for (int d0 = 0; d0 < 4; ++d0) { const float v = o[d0][r] * rli[r];
;             if constexpr (same_t<TOut, float>::v) { Ow[(size_t)orow * (size_t)cur.pitch + d0 * 32 + r32] = v; }
;             else { const float vn = __shfl_xor(v, 1);
;                    if ((r32 & 1) == 0) *(unsigned*)(Ow + (size_t)orow * (size_t)cur.pitch + d0 * 32 + r32) = cvtpk(v, vn); } } }
;     if constexpr (F32) {
; #pragma unroll
;         for (int d0 = 0; d0 < 8; ++d0) S.qr[d0] = pack8(S.tq[2 * d0], S.tq[2 * d0 + 1]); }
;     __syncthreads();
	global_store_dword v1, v74, s[6:7]
	v_mov_b32_dpp v84, v58 quad_perm:[1,0,3,2] row_mask:0xf bank_mask:0xf
	v_mov_b32_dpp v85, v26 quad_perm:[1,0,3,2] row_mask:0xf bank_mask:0xf
	v_cndmask_b32_e64 v58, v58, v85, s[8:9]
	v_cndmask_b32_e64 v26, v84, v26, s[8:9]
	v_cvt_pk_bf16_f32 v58, v58, v26
	global_store_dword v1, v58, s[6:7] offset:64
	v_add_u32_e32 v1, s10, v1
	v_mov_b32_dpp v84, v75 quad_perm:[1,0,3,2] row_mask:0xf bank_mask:0xf
	v_mov_b32_dpp v85, v43 quad_perm:[1,0,3,2] row_mask:0xf bank_mask:0xf
	v_cndmask_b32_e64 v75, v75, v85, s[8:9]
	v_cndmask_b32_e64 v43, v84, v43, s[8:9]
	v_cvt_pk_bf16_f32 v75, v75, v43
	global_store_dword v1, v75, s[6:7]
	v_mov_b32_dpp v84, v59 quad_perm:[1,0,3,2] row_mask:0xf bank_mask:0xf
	v_mov_b32_dpp v85, v27 quad_perm:[1,0,3,2] row_mask:0xf bank_mask:0xf
	v_cndmask_b32_e64 v59, v59, v85, s[8:9]
	v_cndmask_b32_e64 v27, v84, v27, s[8:9]
	v_cvt_pk_bf16_f32 v59, v59, v27
	global_store_dword v1, v59, s[6:7] offset:64
	v_add_u32_e32 v1, s11, v1
	v_mov_b32_dpp v84, v76 quad_perm:[1,0,3,2] row_mask:0xf bank_mask:0xf
	v_mov_b32_dpp v85, v44 quad_perm:[1,0,3,2] row_mask:0xf bank_mask:0xf
	v_cndmask_b32_e64 v76, v76, v85, s[8:9]
	v_cndmask_b32_e64 v44, v84, v44, s[8:9]
	v_cvt_pk_bf16_f32 v76, v76, v44
	global_store_dword v1, v76, s[6:7]
	v_mov_b32_dpp v84, v60 quad_perm:[1,0,3,2] row_mask:0xf bank_mask:0xf
	v_mov_b32_dpp v85, v28 quad_perm:[1,0,3,2] row_mask:0xf bank_mask:0xf
	v_cndmask_b32_e64 v60, v60, v85, s[8:9]
	v_cndmask_b32_e64 v28, v84, v28, s[8:9]
	v_cvt_pk_bf16_f32 v60, v60, v28
	global_store_dword v1, v60, s[6:7] offset:64
	v_add_u32_e32 v1, s10, v1
	v_mov_b32_dpp v84, v77 quad_perm:[1,0,3,2] row_mask:0xf bank_mask:0xf
	v_mov_b32_dpp v85, v45 quad_perm:[1,0,3,2] row_mask:0xf bank_mask:0xf
	v_cndmask_b32_e64 v77, v77, v85, s[8:9]
	v_cndmask_b32_e64 v45, v84, v45, s[8:9]
	v_cvt_pk_bf16_f32 v77, v77, v45
	global_store_dword v1, v77, s[6:7]
	v_mov_b32_dpp v84, v61 quad_perm:[1,0,3,2] row_mask:0xf bank_mask:0xf
	v_mov_b32_dpp v85, v29 quad_perm:[1,0,3,2] row_mask:0xf bank_mask:0xf
	v_cndmask_b32_e64 v61, v61, v85, s[8:9]
	v_cndmask_b32_e64 v29, v84, v29, s[8:9]
	v_cvt_pk_bf16_f32 v61, v61, v29
	global_store_dword v1, v61, s[6:7] offset:64
	v_add_u32_e32 v1, s10, v1
	v_mov_b32_dpp v84, v78 quad_perm:[1,0,3,2] row_mask:0xf bank_mask:0xf
	v_mov_b32_dpp v85, v46 quad_perm:[1,0,3,2] row_mask:0xf bank_mask:0xf
	v_cndmask_b32_e64 v78, v78, v85, s[8:9]
	v_cndmask_b32_e64 v46, v84, v46, s[8:9]
	v_cvt_pk_bf16_f32 v78, v78, v46
	global_store_dword v1, v78, s[6:7]
	v_mov_b32_dpp v84, v62 quad_perm:[1,0,3,2] row_mask:0xf bank_mask:0xf
	v_mov_b32_dpp v85, v30 quad_perm:[1,0,3,2] row_mask:0xf bank_mask:0xf
	v_cndmask_b32_e64 v62, v62, v85, s[8:9]
	v_cndmask_b32_e64 v30, v84, v30, s[8:9]
	v_cvt_pk_bf16_f32 v62, v62, v30
	global_store_dword v1, v62, s[6:7] offset:64
	v_add_u32_e32 v1, s10, v1
	v_mov_b32_dpp v84, v79 quad_perm:[1,0,3,2] row_mask:0xf bank_mask:0xf
	v_mov_b32_dpp v85, v47 quad_perm:[1,0,3,2] row_mask:0xf bank_mask:0xf
	v_cndmask_b32_e64 v79, v79, v85, s[8:9]
	v_cndmask_b32_e64 v47, v84, v47, s[8:9]
	v_cvt_pk_bf16_f32 v79, v79, v47
	global_store_dword v1, v79, s[6:7]
	v_mov_b32_dpp v84, v63 quad_perm:[1,0,3,2] row_mask:0xf bank_mask:0xf
	v_mov_b32_dpp v85, v31 quad_perm:[1,0,3,2] row_mask:0xf bank_mask:0xf
	v_cndmask_b32_e64 v63, v63, v85, s[8:9]
	v_cndmask_b32_e64 v31, v84, v31, s[8:9]
	v_cvt_pk_bf16_f32 v63, v63, v31
	global_store_dword v1, v63, s[6:7] offset:64
	s_andn2_b64 vcc, exec, s[24:25]
	s_waitcnt lgkmcnt(0)
	s_barrier
	s_cbranch_vccz .LBB0_216
	s_mov_b32 s49, s48
	s_and_b64 vcc, exec, s[22:23]
	s_mov_b32 s48, s49
	s_cbranch_vccz .LBB0_217
